# P8->P9 barrier split: conv-done arrival inside P8 (XCD-leader writeback) checked at P9 start, end-of-P8 arrival checked in first P9 K sequence
# baseline (speedup 1.0000x reference)
.LBB0_1125:
	s_or_b64 exec, exec, s[18:19]
	s_waitcnt vmcnt(0)
	s_barrier
	s_and_saveexec_b64 s[100:101], s[92:93]
	s_cbranch_execz .Lp8c_end
	v_mov_b32_e32 v2, 0x22000
	ds_read_b32 v4, v2
	s_lshl_b32 s0, s87, 8
	s_add_i32 s0, s0, 0x2b5d034
	v_mov_b32_e32 v2, s0
	v_mov_b32_e32 v3, 1
	global_atomic_add v6, v2, v3, s[88:89] sc0
	s_waitcnt vmcnt(0) lgkmcnt(0)
	v_add_u32_e32 v6, 1, v6
	v_cmp_eq_u32_e32 vcc, v6, v4
	s_cbranch_vccz .Lp8c_end
	buffer_wbl2 sc1
	s_waitcnt vmcnt(0)
	v_mov_b32_e32 v2, 0x2b5d038
	global_atomic_add v2, v3, s[88:89]
.Lp8c_end:
	s_or_b64 exec, exec, s[100:101]
	v_readlane_b32 s0, v254, 5
	v_readlane_b32 s1, v254, 6
	s_and_b64 vcc, exec, s[0:1]
	s_cbranch_vccnz .LBB0_1173
	s_load_dwordx2 s[12:13], s[96:97], 0xe8
	v_readlane_b32 s0, v254, 9
	v_readlane_b32 s1, v254, 10
	s_ashr_i32 s1, s0, 31
	v_mov_b32_e32 v30, v0
	s_lshl_b64 s[18:19], s[0:1], 19
	s_lshl_b32 s3, s37, 9
	s_ashr_i32 s20, s2, 7
	v_bfe_i32 v4, v30, 27, 1
	s_or_b32 s18, s18, s3
	v_lshlrev_b32_e32 v2, 4, v30
	v_lshrrev_b32_e32 v4, 22, v4
	s_waitcnt lgkmcnt(0)
	s_add_u32 s0, s12, s18
	v_add_u32_e32 v4, v2, v4
	s_addc_u32 s1, s13, s19
	v_and_b32_e32 v4, 0xfffffc00, v4
	s_add_u32 s4, s0, 0x4e00000
	v_sub_u32_e32 v2, v2, v4
	s_addc_u32 s5, s1, 0
	s_ashr_i32 s21, s20, 31
	v_ashrrev_i32_e32 v3, 31, v30
	v_lshrrev_b32_e32 v4, 4, v2
	s_lshl_b64 s[0:1], s[20:21], 19
	v_lshrrev_b32_e32 v3, 26, v3
	v_bitop3_b32 v2, v4, v2, 32 bitop3:0x6c
	s_add_u32 s0, s12, s0
	v_add_u32_e32 v3, v30, v3
	v_ashrrev_i32_e32 v5, 31, v2
	s_addc_u32 s1, s13, s1
	v_ashrrev_i32_e32 v3, 6, v3
	v_lshrrev_b32_e32 v5, 26, v5
	s_add_u32 s0, s0, s3
	v_lshlrev_b32_e32 v4, 3, v3
	v_add_u32_e32 v5, v2, v5
	s_addc_u32 s1, s1, 0
	v_and_b32_e32 v4, -16, v4
	v_ashrrev_i32_e32 v6, 6, v5
	v_and_b32_e32 v5, 0xc0, v5
	s_add_u32 s8, s0, 0x2559000
	v_readfirstlane_b32 s0, v30
	v_add_u32_e32 v4, v6, v4
	v_sub_u32_e32 v2, v2, v5
	v_mov_b32_e32 v5, 1
	s_addc_u32 s9, s1, 0
	s_ashr_i32 s6, s0, 6
	v_lshlrev_b32_e32 v3, 5, v3
	v_ashrrev_i16_sdwa v2, v5, sext(v2) dst_sel:DWORD dst_unused:UNUSED_PAD src0_sel:DWORD src1_sel:BYTE_0
	v_lshlrev_b32_e32 v5, 1, v4
	v_lshrrev_b32_e32 v7, 2, v4
	v_and_b32_e32 v6, 3, v6
	s_mov_b32 s1, 0x1fffe0
	v_and_b32_e32 v3, 32, v3
	v_bfe_i32 v2, v2, 0, 16
	v_and_b32_e32 v5, 24, v5
	v_and_b32_e32 v7, 4, v7
	v_and_or_b32 v6, v4, s1, v6
	s_lshl_b32 s25, s6, 10
	v_or3_b32 v5, v6, v7, v5
	v_add_lshl_u32 v3, v3, v2, 1
	s_add_i32 s23, s25, 0
	v_lshl_add_u32 v2, v4, 11, v3
	v_lshl_add_u32 v4, v5, 11, v3
	v_mov_b32_e32 v5, 0
	s_add_i32 m0, s23, 0x10000
	v_lshl_add_u64 v[26:27], s[8:9], 0, v[4:5]
	global_load_lds_dwordx4 v4, s[8:9]
	s_mov_b64 s[8:9], 0x20000
	v_lshl_add_u64 v[28:29], v[26:27], 0, s[8:9]
	s_add_i32 m0, s23, 0x12000
	v_mov_b32_e32 v3, v5
	global_load_lds_dwordx4 v[28:29], off
	v_lshl_add_u64 v[22:23], s[4:5], 0, v[2:3]
	s_mov_b32 m0, s23
	s_add_i32 s24, s23, 0x2000
	global_load_lds_dwordx4 v2, s[4:5]
	v_lshl_add_u64 v[24:25], v[22:23], 0, s[8:9]
	s_mov_b32 m0, s24
	s_mov_b64 s[4:5], 0x40000
	global_load_lds_dwordx4 v[24:25], off
	v_lshl_add_u64 v[18:19], v[26:27], 0, s[4:5]
	s_add_i32 m0, s23, 0x14000
	s_mov_b64 s[8:9], 0x60000
	global_load_lds_dwordx4 v[18:19], off
	v_lshl_add_u64 v[20:21], v[26:27], 0, s[8:9]
	s_add_i32 m0, s23, 0x16000
	s_add_i32 s14, s23, 0x4000
	global_load_lds_dwordx4 v[20:21], off
	v_lshl_add_u64 v[8:9], v[22:23], 0, s[4:5]
	s_mov_b32 m0, s14
	s_add_i32 s21, s23, 0x6000
	global_load_lds_dwordx4 v[8:9], off
	v_lshl_add_u64 v[14:15], v[22:23], 0, s[8:9]
	s_mov_b32 m0, s21
	s_ashr_i32 s3, s0, 8
	global_load_lds_dwordx4 v[14:15], off
	s_cmp_lg_u32 s3, 1
	s_cbranch_scc1 .LBB0_1128
	s_barrier

.LBB0_1173:
	s_waitcnt vmcnt(0)
	s_barrier
	s_and_saveexec_b64 s[10:11], s[92:93]
	s_cbranch_execz .LBB0_1225
	v_mov_b32_e32 v2, 0x2b5d03c
	v_mov_b32_e32 v3, 1
	global_atomic_add v2, v3, s[88:89]
	v_mov_b32_e32 v2, 0x22004
	ds_read_b32 v4, v2
	v_mov_b32_e32 v2, 0x2b5d038
	s_mov_b32 s1, 0x100000
	s_waitcnt lgkmcnt(0)
.Lp9s_poll:
	global_load_dword v3, v2, s[88:89] sc1
	s_waitcnt vmcnt(0)
	v_cmp_ge_u32_e32 vcc, v3, v4
	s_cbranch_vccnz .Lp9s_done
	s_sleep 1
	s_sub_u32 s1, s1, 1
	s_cmp_lg_u32 s1, 0
	s_cbranch_scc1 .Lp9s_poll

.LBB0_1225:
	s_or_b64 exec, exec, s[10:11]
	v_mov_b32_e32 v170, v0
	s_waitcnt lgkmcnt(0)
	s_barrier
	s_mov_b32 s100, 1
	s_load_dwordx2 s[46:47], s[96:97], 0xe8
	v_mov_b32_e32 v6, v0
	v_cndmask_b32_e64 v2, 0, 1, s[16:17]
	v_cmp_ne_u32_e64 s[10:11], 1, v2
	s_waitcnt lgkmcnt(0)
	s_add_u32 s18, s46, 0x8e00000
	s_addc_u32 s19, s47, 0
	s_add_u32 s3, s46, 0x2000000
	s_addc_u32 s35, s47, 0
	s_andn2_b64 vcc, exec, s[16:17]
	v_readfirstlane_b32 s0, v6
	s_cbranch_vccnz .LBB0_1227
	s_and_b32 s1, s83, 56
	s_ashr_i32 s4, s2, 6
	s_add_i32 s4, s1, s4
	s_ashr_i32 s5, s4, 31
	s_lshl_b32 s1, s2, 5
	s_lshl_b64 s[6:7], s[4:5], 19
	s_and_b32 s1, s1, 0x600
	s_add_u32 s5, s18, s6
	s_addc_u32 s6, s19, s7
	s_add_u32 s76, s5, s1
	s_addc_u32 s77, s6, 0
	s_lshl_b32 s1, s2, 14
	s_and_b32 s1, s1, 0xe0000
	s_add_u32 s72, s3, s1
	s_addc_u32 s73, s35, 0
	s_lshl_b32 s1, s2, 4
	s_lshl_b32 s27, s4, 8
	s_and_b32 s26, s1, 0x380
	s_and_b64 vcc, exec, s[10:11]
	s_cbranch_vccz .LBB0_1228
	s_branch .LBB0_1497

.LBB0_1235:
	ds_read_b128 v[4:7], v174
	ds_read_b128 v[8:11], v174 offset:1024
	ds_read_b128 v[12:15], v174 offset:2048
	ds_read_b128 v[16:19], v174 offset:3072
	v_lshl_add_u64 v[2:3], s[76:77], 0, v[142:143]
	s_mov_b64 s[0:1], 0x40080
	s_add_i32 vcc_lo, s78, 0xc000
	v_lshl_add_u64 v[52:53], v[2:3], 0, s[0:1]
	s_mov_b32 m0, vcc_lo
	s_mov_b64 s[0:1], 0x60080
	ds_read_b128 v[20:23], v175
	ds_read_b128 v[24:27], v175 offset:1024
	ds_read_b128 v[28:31], v175 offset:2048
	ds_read_b128 v[32:35], v175 offset:3072
	ds_read_b128 v[36:39], v175 offset:4096
	ds_read_b128 v[40:43], v175 offset:5120
	ds_read_b128 v[44:47], v175 offset:6144
	ds_read_b128 v[48:51], v175 offset:7168
	global_load_lds_dwordx4 v[52:53], off
	v_lshl_add_u64 v[52:53], v[2:3], 0, s[0:1]
	s_add_i32 s1, s78, 0xe000
	s_mov_b32 m0, s1
	s_nop 0
	global_load_lds_dwordx4 v[52:53], off
	s_waitcnt lgkmcnt(8)
	s_barrier
	s_waitcnt lgkmcnt(0)
	s_setprio 1
	s_waitcnt lgkmcnt(0)
	v_mfma_f32_16x16x32_bf16 v[52:55], v[4:7], v[20:23], 0
	v_mfma_f32_16x16x32_bf16 v[56:59], v[12:15], v[20:23], 0
	v_mfma_f32_16x16x32_bf16 v[60:63], v[4:7], v[28:31], 0
	v_mfma_f32_16x16x32_bf16 v[64:67], v[12:15], v[28:31], 0
	v_mfma_f32_16x16x32_bf16 v[68:71], v[4:7], v[36:39], 0
	v_mfma_f32_16x16x32_bf16 v[72:75], v[12:15], v[36:39], 0
	v_mfma_f32_16x16x32_bf16 v[76:79], v[4:7], v[44:47], 0
	v_mfma_f32_16x16x32_bf16 v[80:83], v[12:15], v[44:47], 0
	v_mfma_f32_16x16x32_bf16 v[52:55], v[8:11], v[24:27], v[52:55]
	v_mfma_f32_16x16x32_bf16 v[56:59], v[16:19], v[24:27], v[56:59]
	v_mfma_f32_16x16x32_bf16 v[60:63], v[8:11], v[32:35], v[60:63]
	v_mfma_f32_16x16x32_bf16 v[64:67], v[16:19], v[32:35], v[64:67]
	v_mfma_f32_16x16x32_bf16 v[68:71], v[8:11], v[40:43], v[68:71]
	v_mfma_f32_16x16x32_bf16 v[72:75], v[16:19], v[40:43], v[72:75]
	v_mfma_f32_16x16x32_bf16 v[76:79], v[8:11], v[48:51], v[76:79]
	v_mfma_f32_16x16x32_bf16 v[80:83], v[16:19], v[48:51], v[80:83]
	s_setprio 0
	s_barrier
	v_lshl_add_u64 v[140:141], s[72:73], 0, v[144:145]
	s_add_i32 s73, s95, s37
	v_lshl_add_u64 v[100:101], v[140:141], 0, s[60:61]
	s_mov_b32 m0, s73
	s_mov_b64 s[30:31], 0x8100
	s_add_i32 s72, s73, 0x2000
	ds_read_b128 v[84:87], v176
	ds_read_b128 v[88:91], v176 offset:1024
	ds_read_b128 v[92:95], v176 offset:2048
	ds_read_b128 v[96:99], v176 offset:3072
	global_load_lds_dwordx4 v[100:101], off
	v_lshl_add_u64 v[100:101], v[140:141], 0, s[30:31]
	s_mov_b32 m0, s72
	s_nop 0
	global_load_lds_dwordx4 v[100:101], off
	s_barrier
	s_waitcnt lgkmcnt(0)
	s_setprio 1
	s_waitcnt lgkmcnt(0)
	v_mfma_f32_16x16x32_bf16 v[100:103], v[84:87], v[20:23], 0
	v_mfma_f32_16x16x32_bf16 v[20:23], v[92:95], v[20:23], 0
	v_mfma_f32_16x16x32_bf16 v[100:103], v[88:91], v[24:27], v[100:103]
	v_mfma_f32_16x16x32_bf16 v[20:23], v[96:99], v[24:27], v[20:23]
	v_mfma_f32_16x16x32_bf16 v[24:27], v[84:87], v[28:31], 0
	v_mfma_f32_16x16x32_bf16 v[28:31], v[92:95], v[28:31], 0
	v_mfma_f32_16x16x32_bf16 v[24:27], v[88:91], v[32:35], v[24:27]
	v_mfma_f32_16x16x32_bf16 v[28:31], v[96:99], v[32:35], v[28:31]
	v_mfma_f32_16x16x32_bf16 v[32:35], v[84:87], v[36:39], 0
	v_mfma_f32_16x16x32_bf16 v[36:39], v[92:95], v[36:39], 0
	v_mfma_f32_16x16x32_bf16 v[32:35], v[88:91], v[40:43], v[32:35]
	v_mfma_f32_16x16x32_bf16 v[36:39], v[96:99], v[40:43], v[36:39]
	v_mfma_f32_16x16x32_bf16 v[40:43], v[84:87], v[44:47], 0
	v_mfma_f32_16x16x32_bf16 v[44:47], v[92:95], v[44:47], 0
	v_mfma_f32_16x16x32_bf16 v[40:43], v[88:91], v[48:51], v[40:43]
	v_mfma_f32_16x16x32_bf16 v[44:47], v[96:99], v[48:51], v[44:47]
	s_setprio 0
	s_mov_b32 m0, s78
	v_lshl_add_u64 v[132:133], v[2:3], 0, s[60:61]
	s_mov_b64 s[30:31], 0x20100
	s_barrier
	ds_read_b128 v[48:51], v175 offset:16384
	ds_read_b128 v[104:107], v175 offset:17408
	ds_read_b128 v[108:111], v175 offset:18432
	ds_read_b128 v[112:115], v175 offset:19456
	ds_read_b128 v[116:119], v175 offset:20480
	ds_read_b128 v[120:123], v175 offset:21504
	ds_read_b128 v[124:127], v175 offset:22528
	ds_read_b128 v[128:131], v175 offset:23552
	global_load_lds_dwordx4 v[132:133], off
	v_lshl_add_u64 v[132:133], v[2:3], 0, s[30:31]
	s_mov_b32 m0, s79
	s_nop 0
	global_load_lds_dwordx4 v[132:133], off
	s_barrier
	s_waitcnt lgkmcnt(0)
	s_setprio 1
	s_waitcnt lgkmcnt(0)
	v_mfma_f32_16x16x32_bf16 v[132:135], v[4:7], v[48:51], 0
	v_mfma_f32_16x16x32_bf16 v[148:151], v[4:7], v[108:111], 0
	v_mfma_f32_16x16x32_bf16 v[156:159], v[4:7], v[116:119], 0
	v_mfma_f32_16x16x32_bf16 v[4:7], v[4:7], v[124:127], 0
	v_mfma_f32_16x16x32_bf16 v[132:135], v[8:11], v[104:107], v[132:135]
	v_mfma_f32_16x16x32_bf16 v[136:139], v[12:15], v[48:51], 0
	v_mfma_f32_16x16x32_bf16 v[148:151], v[8:11], v[112:115], v[148:151]
	v_mfma_f32_16x16x32_bf16 v[156:159], v[8:11], v[120:123], v[156:159]
	v_mfma_f32_16x16x32_bf16 v[4:7], v[8:11], v[128:131], v[4:7]
	v_mfma_f32_16x16x32_bf16 v[8:11], v[12:15], v[124:127], 0
	v_mfma_f32_16x16x32_bf16 v[136:139], v[16:19], v[104:107], v[136:139]
	v_mfma_f32_16x16x32_bf16 v[152:155], v[12:15], v[108:111], 0
	v_mfma_f32_16x16x32_bf16 v[160:163], v[12:15], v[116:119], 0
	v_mfma_f32_16x16x32_bf16 v[8:11], v[16:19], v[128:131], v[8:11]
	v_mfma_f32_16x16x32_bf16 v[152:155], v[16:19], v[112:115], v[152:155]
	v_mfma_f32_16x16x32_bf16 v[160:163], v[16:19], v[120:123], v[160:163]
	s_setprio 0
	s_barrier
	s_mov_b64 s[30:31], 0x10100
	s_add_i32 s76, s96, s37
	v_lshl_add_u64 v[12:13], v[140:141], 0, s[30:31]
	s_mov_b32 m0, s76
	s_mov_b64 s[30:31], 0x18100
	s_add_i32 s77, s76, 0x2000
	global_load_lds_dwordx4 v[12:13], off
	v_lshl_add_u64 v[12:13], v[140:141], 0, s[30:31]
	s_mov_b32 m0, s77
	s_nop 0
	global_load_lds_dwordx4 v[12:13], off
	s_waitcnt vmcnt(6)
	s_barrier
	s_setprio 1
	v_mfma_f32_16x16x32_bf16 v[12:15], v[84:87], v[48:51], 0
	v_mfma_f32_16x16x32_bf16 v[16:19], v[92:95], v[48:51], 0
	v_mfma_f32_16x16x32_bf16 v[12:15], v[88:91], v[104:107], v[12:15]
	v_mfma_f32_16x16x32_bf16 v[16:19], v[96:99], v[104:107], v[16:19]
	v_mfma_f32_16x16x32_bf16 v[48:51], v[84:87], v[108:111], 0
	v_mfma_f32_16x16x32_bf16 v[104:107], v[92:95], v[108:111], 0
	v_mfma_f32_16x16x32_bf16 v[108:111], v[84:87], v[116:119], 0
	v_mfma_f32_16x16x32_bf16 v[84:87], v[84:87], v[124:127], 0
	v_mfma_f32_16x16x32_bf16 v[48:51], v[88:91], v[112:115], v[48:51]
	v_mfma_f32_16x16x32_bf16 v[104:107], v[96:99], v[112:115], v[104:107]
	v_mfma_f32_16x16x32_bf16 v[108:111], v[88:91], v[120:123], v[108:111]
	v_mfma_f32_16x16x32_bf16 v[112:115], v[92:95], v[116:119], 0
	v_mfma_f32_16x16x32_bf16 v[84:87], v[88:91], v[128:131], v[84:87]
	v_mfma_f32_16x16x32_bf16 v[88:91], v[92:95], v[124:127], 0
	v_mfma_f32_16x16x32_bf16 v[112:115], v[96:99], v[120:123], v[112:115]
	v_mfma_f32_16x16x32_bf16 v[88:91], v[96:99], v[128:131], v[88:91]
	s_setprio 0
	s_add_i32 vcc_hi, 0, 0x18000
	v_add_u32_e32 v147, vcc_hi, v173
	s_barrier
	ds_read_b128 v[92:95], v147
	ds_read_b128 v[96:99], v147 offset:1024
	ds_read_b128 v[116:119], v147 offset:2048
	ds_read_b128 v[120:123], v147 offset:3072
	s_mov_b64 s[30:31], 0x40100
	s_mov_b32 m0, s80
	v_lshl_add_u64 v[168:169], v[2:3], 0, s[30:31]
	s_mov_b64 s[30:31], 0x60100
	ds_read_b128 v[124:127], v175 offset:32768
	ds_read_b128 v[128:131], v175 offset:33792
	ds_read_b128 v[164:167], v175 offset:34816
	ds_read_b128 v[180:183], v175 offset:35840
	ds_read_b128 v[184:187], v175 offset:36864
	ds_read_b128 v[188:191], v175 offset:37888
	ds_read_b128 v[192:195], v175 offset:38912
	ds_read_b128 v[196:199], v175 offset:39936
	global_load_lds_dwordx4 v[168:169], off
	v_lshl_add_u64 v[168:169], v[2:3], 0, s[30:31]
	s_mov_b32 m0, s81
	s_nop 0
	global_load_lds_dwordx4 v[168:169], off
	s_waitcnt lgkmcnt(8)
	s_barrier
	s_waitcnt lgkmcnt(0)
	s_setprio 1
	s_waitcnt lgkmcnt(0)
	v_mfma_f32_16x16x32_bf16 v[52:55], v[92:95], v[124:127], v[52:55]
	v_mfma_f32_16x16x32_bf16 v[56:59], v[116:119], v[124:127], v[56:59]
	v_mfma_f32_16x16x32_bf16 v[60:63], v[92:95], v[164:167], v[60:63]
	v_mfma_f32_16x16x32_bf16 v[64:67], v[116:119], v[164:167], v[64:67]
	v_mfma_f32_16x16x32_bf16 v[68:71], v[92:95], v[184:187], v[68:71]
	v_mfma_f32_16x16x32_bf16 v[72:75], v[116:119], v[184:187], v[72:75]
	v_mfma_f32_16x16x32_bf16 v[76:79], v[92:95], v[192:195], v[76:79]
	v_mfma_f32_16x16x32_bf16 v[80:83], v[116:119], v[192:195], v[80:83]
	v_mfma_f32_16x16x32_bf16 v[52:55], v[96:99], v[128:131], v[52:55]
	v_mfma_f32_16x16x32_bf16 v[56:59], v[120:123], v[128:131], v[56:59]
	v_mfma_f32_16x16x32_bf16 v[60:63], v[96:99], v[180:183], v[60:63]
	v_mfma_f32_16x16x32_bf16 v[64:67], v[120:123], v[180:183], v[64:67]
	v_mfma_f32_16x16x32_bf16 v[68:71], v[96:99], v[188:191], v[68:71]
	v_mfma_f32_16x16x32_bf16 v[72:75], v[120:123], v[188:191], v[72:75]
	v_mfma_f32_16x16x32_bf16 v[76:79], v[96:99], v[196:199], v[76:79]
	v_mfma_f32_16x16x32_bf16 v[80:83], v[120:123], v[196:199], v[80:83]
	s_setprio 0
	s_barrier
	s_add_i32 s10, 0, 0x1c000
	s_add_i32 vcc_hi, vcc_hi, s37
	v_add_u32_e32 v179, s10, v173
	v_lshl_add_u64 v[168:169], v[140:141], 0, s[62:63]
	s_mov_b32 m0, vcc_hi
	s_mov_b64 s[30:31], 0x8180
	s_add_i32 s0, vcc_hi, 0x2000
	ds_read_b128 v[200:203], v179
	ds_read_b128 v[204:207], v179 offset:1024
	ds_read_b128 v[208:211], v179 offset:2048
	ds_read_b128 v[212:215], v179 offset:3072
	global_load_lds_dwordx4 v[168:169], off
	v_lshl_add_u64 v[168:169], v[140:141], 0, s[30:31]
	s_mov_b32 m0, s0
	s_nop 0
	global_load_lds_dwordx4 v[168:169], off
	s_barrier
	s_waitcnt lgkmcnt(0)
	s_setprio 1
	s_waitcnt lgkmcnt(0)
	v_mfma_f32_16x16x32_bf16 v[100:103], v[200:203], v[124:127], v[100:103]
	v_mfma_f32_16x16x32_bf16 v[20:23], v[208:211], v[124:127], v[20:23]
	v_mfma_f32_16x16x32_bf16 v[24:27], v[200:203], v[164:167], v[24:27]
	v_mfma_f32_16x16x32_bf16 v[28:31], v[208:211], v[164:167], v[28:31]
	v_mfma_f32_16x16x32_bf16 v[32:35], v[200:203], v[184:187], v[32:35]
	v_mfma_f32_16x16x32_bf16 v[36:39], v[208:211], v[184:187], v[36:39]
	v_mfma_f32_16x16x32_bf16 v[40:43], v[200:203], v[192:195], v[40:43]
	v_mfma_f32_16x16x32_bf16 v[44:47], v[208:211], v[192:195], v[44:47]
	v_mfma_f32_16x16x32_bf16 v[100:103], v[204:207], v[128:131], v[100:103]
	v_mfma_f32_16x16x32_bf16 v[20:23], v[212:215], v[128:131], v[20:23]
	v_mfma_f32_16x16x32_bf16 v[24:27], v[204:207], v[180:183], v[24:27]
	v_mfma_f32_16x16x32_bf16 v[28:31], v[212:215], v[180:183], v[28:31]
	v_mfma_f32_16x16x32_bf16 v[32:35], v[204:207], v[188:191], v[32:35]
	v_mfma_f32_16x16x32_bf16 v[36:39], v[212:215], v[188:191], v[36:39]
	v_mfma_f32_16x16x32_bf16 v[40:43], v[204:207], v[196:199], v[40:43]
	v_mfma_f32_16x16x32_bf16 v[44:47], v[212:215], v[196:199], v[44:47]
	s_setprio 0
	s_mov_b32 m0, s83
	v_lshl_add_u64 v[168:169], v[2:3], 0, s[62:63]
	s_mov_b64 s[30:31], 0x20180
	s_barrier
	ds_read_b128 v[124:127], v175 offset:49152
	ds_read_b128 v[128:131], v175 offset:50176
	ds_read_b128 v[164:167], v175 offset:51200
	ds_read_b128 v[180:183], v175 offset:52224
	ds_read_b128 v[184:187], v175 offset:53248
	ds_read_b128 v[188:191], v175 offset:54272
	ds_read_b128 v[192:195], v175 offset:55296
	ds_read_b128 v[196:199], v175 offset:56320
	global_load_lds_dwordx4 v[168:169], off
	v_lshl_add_u64 v[168:169], v[2:3], 0, s[30:31]
	s_mov_b32 m0, s87
	s_nop 0
	global_load_lds_dwordx4 v[168:169], off
	s_barrier
	s_waitcnt lgkmcnt(0)
	s_setprio 1
	s_waitcnt lgkmcnt(0)
	v_mfma_f32_16x16x32_bf16 v[132:135], v[92:95], v[124:127], v[132:135]
	v_mfma_f32_16x16x32_bf16 v[136:139], v[116:119], v[124:127], v[136:139]
	v_mfma_f32_16x16x32_bf16 v[4:7], v[92:95], v[192:195], v[4:7]
	v_mfma_f32_16x16x32_bf16 v[8:11], v[116:119], v[192:195], v[8:11]
	v_mfma_f32_16x16x32_bf16 v[132:135], v[96:99], v[128:131], v[132:135]
	v_mfma_f32_16x16x32_bf16 v[136:139], v[120:123], v[128:131], v[136:139]
	v_mfma_f32_16x16x32_bf16 v[148:151], v[92:95], v[164:167], v[148:151]
	v_mfma_f32_16x16x32_bf16 v[152:155], v[116:119], v[164:167], v[152:155]
	v_mfma_f32_16x16x32_bf16 v[156:159], v[92:95], v[184:187], v[156:159]
	v_mfma_f32_16x16x32_bf16 v[160:163], v[116:119], v[184:187], v[160:163]
	v_mfma_f32_16x16x32_bf16 v[4:7], v[96:99], v[196:199], v[4:7]
	v_mfma_f32_16x16x32_bf16 v[8:11], v[120:123], v[196:199], v[8:11]
	v_mfma_f32_16x16x32_bf16 v[148:151], v[96:99], v[180:183], v[148:151]
	v_mfma_f32_16x16x32_bf16 v[152:155], v[120:123], v[180:183], v[152:155]
	v_mfma_f32_16x16x32_bf16 v[156:159], v[96:99], v[188:191], v[156:159]
	v_mfma_f32_16x16x32_bf16 v[160:163], v[120:123], v[188:191], v[160:163]
	s_setprio 0
	s_barrier
	s_mov_b64 s[30:31], 0x10180
	v_lshl_add_u64 v[92:93], v[140:141], 0, s[30:31]
	s_add_i32 s30, s10, s37
	s_mov_b32 m0, s30
	s_mov_b64 s[10:11], 0x18180
	s_add_i32 s31, s30, 0x2000
	global_load_lds_dwordx4 v[92:93], off
	v_lshl_add_u64 v[92:93], v[140:141], 0, s[10:11]
	s_mov_b32 m0, s31
	s_nop 0
	global_load_lds_dwordx4 v[92:93], off
	s_waitcnt vmcnt(6)
	s_barrier
	s_setprio 1
	v_mfma_f32_16x16x32_bf16 v[12:15], v[200:203], v[124:127], v[12:15]
	v_mfma_f32_16x16x32_bf16 v[16:19], v[208:211], v[124:127], v[16:19]
	v_mfma_f32_16x16x32_bf16 v[48:51], v[200:203], v[164:167], v[48:51]
	v_mfma_f32_16x16x32_bf16 v[92:95], v[208:211], v[164:167], v[104:107]
	v_mfma_f32_16x16x32_bf16 v[96:99], v[200:203], v[184:187], v[108:111]
	v_mfma_f32_16x16x32_bf16 v[104:107], v[208:211], v[184:187], v[112:115]
	v_mfma_f32_16x16x32_bf16 v[84:87], v[200:203], v[192:195], v[84:87]
	v_mfma_f32_16x16x32_bf16 v[88:91], v[208:211], v[192:195], v[88:91]
	v_mfma_f32_16x16x32_bf16 v[12:15], v[204:207], v[128:131], v[12:15]
	v_mfma_f32_16x16x32_bf16 v[16:19], v[212:215], v[128:131], v[16:19]
	v_mfma_f32_16x16x32_bf16 v[48:51], v[204:207], v[180:183], v[48:51]
	v_mfma_f32_16x16x32_bf16 v[92:95], v[212:215], v[180:183], v[92:95]
	v_mfma_f32_16x16x32_bf16 v[96:99], v[204:207], v[188:191], v[96:99]
	v_mfma_f32_16x16x32_bf16 v[104:107], v[212:215], v[188:191], v[104:107]
	v_mfma_f32_16x16x32_bf16 v[84:87], v[204:207], v[196:199], v[84:87]
	v_mfma_f32_16x16x32_bf16 v[88:91], v[212:215], v[196:199], v[88:91]
	s_setprio 0
	s_barrier
	ds_read_b128 v[108:111], v174
	ds_read_b128 v[112:115], v174 offset:1024
	ds_read_b128 v[116:119], v174 offset:2048
	ds_read_b128 v[120:123], v174 offset:3072
	s_mov_b64 s[10:11], 0x40180
	s_mov_b32 m0, vcc_lo
	v_lshl_add_u64 v[140:141], v[2:3], 0, s[10:11]
	s_mov_b64 s[10:11], 0x60180
	ds_read_b128 v[124:127], v175
	ds_read_b128 v[128:131], v175 offset:1024
	ds_read_b128 v[164:167], v175 offset:2048
	ds_read_b128 v[180:183], v175 offset:3072
	ds_read_b128 v[184:187], v175 offset:4096
	ds_read_b128 v[188:191], v175 offset:5120
	ds_read_b128 v[192:195], v175 offset:6144
	ds_read_b128 v[196:199], v175 offset:7168
	global_load_lds_dwordx4 v[140:141], off
	v_lshl_add_u64 v[2:3], v[2:3], 0, s[10:11]
	s_mov_b32 m0, s1
	s_nop 0
	global_load_lds_dwordx4 v[2:3], off
	s_waitcnt lgkmcnt(8)
	s_barrier
	s_waitcnt lgkmcnt(0)
	s_setprio 1
	s_waitcnt lgkmcnt(0)
	v_mfma_f32_16x16x32_bf16 v[52:55], v[108:111], v[124:127], v[52:55]
	v_mfma_f32_16x16x32_bf16 v[56:59], v[116:119], v[124:127], v[56:59]
	v_mfma_f32_16x16x32_bf16 v[60:63], v[108:111], v[164:167], v[60:63]
	v_mfma_f32_16x16x32_bf16 v[64:67], v[116:119], v[164:167], v[64:67]
	v_mfma_f32_16x16x32_bf16 v[68:71], v[108:111], v[184:187], v[68:71]
	v_mfma_f32_16x16x32_bf16 v[72:75], v[116:119], v[184:187], v[72:75]
	v_mfma_f32_16x16x32_bf16 v[76:79], v[108:111], v[192:195], v[76:79]
	v_mfma_f32_16x16x32_bf16 v[80:83], v[116:119], v[192:195], v[80:83]
	v_mfma_f32_16x16x32_bf16 v[52:55], v[112:115], v[128:131], v[52:55]
	v_mfma_f32_16x16x32_bf16 v[56:59], v[120:123], v[128:131], v[56:59]
	v_mfma_f32_16x16x32_bf16 v[60:63], v[112:115], v[180:183], v[60:63]
	v_mfma_f32_16x16x32_bf16 v[64:67], v[120:123], v[180:183], v[64:67]
	v_mfma_f32_16x16x32_bf16 v[68:71], v[112:115], v[188:191], v[68:71]
	v_mfma_f32_16x16x32_bf16 v[72:75], v[120:123], v[188:191], v[72:75]
	v_mfma_f32_16x16x32_bf16 v[76:79], v[112:115], v[196:199], v[76:79]
	v_mfma_f32_16x16x32_bf16 v[80:83], v[120:123], v[196:199], v[80:83]
	s_setprio 0
	s_barrier
	s_mov_b32 m0, s73
	v_lshl_add_u64 v[168:169], s[74:75], 0, v[144:145]
	s_mov_b64 s[10:11], 0x8000
	ds_read_b128 v[200:203], v176
	ds_read_b128 v[204:207], v176 offset:1024
	ds_read_b128 v[208:211], v176 offset:2048
	ds_read_b128 v[212:215], v176 offset:3072
	global_load_lds_dwordx4 v[168:169], off
	v_lshl_add_u64 v[2:3], v[168:169], 0, s[10:11]
	s_mov_b32 m0, s72
	s_nop 0
	global_load_lds_dwordx4 v[2:3], off
	s_barrier
	s_waitcnt lgkmcnt(0)
	s_setprio 1
	s_waitcnt lgkmcnt(0)
	v_mfma_f32_16x16x32_bf16 v[100:103], v[200:203], v[124:127], v[100:103]
	v_mfma_f32_16x16x32_bf16 v[20:23], v[208:211], v[124:127], v[20:23]
	v_mfma_f32_16x16x32_bf16 v[24:27], v[200:203], v[164:167], v[24:27]
	v_mfma_f32_16x16x32_bf16 v[28:31], v[208:211], v[164:167], v[28:31]
	v_mfma_f32_16x16x32_bf16 v[32:35], v[200:203], v[184:187], v[32:35]
	v_mfma_f32_16x16x32_bf16 v[36:39], v[208:211], v[184:187], v[36:39]
	v_mfma_f32_16x16x32_bf16 v[40:43], v[200:203], v[192:195], v[40:43]
	v_mfma_f32_16x16x32_bf16 v[100:103], v[204:207], v[128:131], v[100:103]
	v_mfma_f32_16x16x32_bf16 v[20:23], v[212:215], v[128:131], v[20:23]
	v_mfma_f32_16x16x32_bf16 v[24:27], v[204:207], v[180:183], v[24:27]
	v_mfma_f32_16x16x32_bf16 v[28:31], v[212:215], v[180:183], v[28:31]
	v_mfma_f32_16x16x32_bf16 v[32:35], v[204:207], v[188:191], v[32:35]
	v_mfma_f32_16x16x32_bf16 v[36:39], v[212:215], v[188:191], v[36:39]
	v_mfma_f32_16x16x32_bf16 v[164:167], v[204:207], v[196:199], v[40:43]
	v_mfma_f32_16x16x32_bf16 v[40:43], v[208:211], v[192:195], v[44:47]
	v_mfma_f32_16x16x32_bf16 v[180:183], v[212:215], v[196:199], v[40:43]
	s_setprio 0
	s_mov_b32 m0, s78
	v_lshl_add_u64 v[252:253], s[70:71], 0, v[142:143]
	s_mov_b64 s[10:11], 0x20000
	s_barrier
	s_nop 1
	ds_read_b128 v[40:43], v175 offset:16384
	ds_read_b128 v[44:47], v175 offset:17408
	ds_read_b128 v[124:127], v175 offset:18432
	ds_read_b128 v[128:131], v175 offset:19456
	ds_read_b128 v[184:187], v175 offset:20480
	ds_read_b128 v[188:191], v175 offset:21504
	ds_read_b128 v[192:195], v175 offset:22528
	ds_read_b128 v[196:199], v175 offset:23552
	global_load_lds_dwordx4 v[252:253], off
	v_lshl_add_u64 v[2:3], v[252:253], 0, s[10:11]
	s_mov_b32 m0, s79
	s_nop 0
	global_load_lds_dwordx4 v[2:3], off
	s_barrier
	s_waitcnt lgkmcnt(0)
	s_setprio 1
	s_waitcnt lgkmcnt(0)
	v_mfma_f32_16x16x32_bf16 v[132:135], v[108:111], v[40:43], v[132:135]
	v_mfma_f32_16x16x32_bf16 v[216:219], v[112:115], v[44:47], v[132:135]
	v_mfma_f32_16x16x32_bf16 v[132:135], v[116:119], v[40:43], v[136:139]
	v_mfma_f32_16x16x32_bf16 v[138:141], v[120:123], v[44:47], v[132:135]
	v_mfma_f32_16x16x32_bf16 v[132:135], v[108:111], v[124:127], v[148:151]
	v_mfma_f32_16x16x32_bf16 v[148:151], v[112:115], v[128:131], v[132:135]
	v_mfma_f32_16x16x32_bf16 v[132:135], v[116:119], v[124:127], v[152:155]
	v_mfma_f32_16x16x32_bf16 v[152:155], v[120:123], v[128:131], v[132:135]
	v_mfma_f32_16x16x32_bf16 v[132:135], v[108:111], v[184:187], v[156:159]
	v_mfma_f32_16x16x32_bf16 v[2:5], v[108:111], v[192:195], v[4:7]
	v_mfma_f32_16x16x32_bf16 v[6:9], v[116:119], v[192:195], v[8:11]
	v_mfma_f32_16x16x32_bf16 v[156:159], v[112:115], v[188:191], v[132:135]
	v_mfma_f32_16x16x32_bf16 v[132:135], v[116:119], v[184:187], v[160:163]
	v_mfma_f32_16x16x32_bf16 v[2:5], v[112:115], v[196:199], v[2:5]
	v_mfma_f32_16x16x32_bf16 v[6:9], v[120:123], v[196:199], v[6:9]
	v_mfma_f32_16x16x32_bf16 v[160:163], v[120:123], v[188:191], v[132:135]
	s_setprio 0
	s_barrier
	s_mov_b32 m0, s76
	v_lshl_add_u64 v[10:11], v[168:169], 0, s[20:21]
	global_load_lds_dwordx4 v[10:11], off
	v_lshl_add_u64 v[10:11], v[168:169], 0, s[22:23]
	s_mov_b32 m0, s77
	s_nop 0
	global_load_lds_dwordx4 v[10:11], off
	s_waitcnt vmcnt(6)
	s_barrier
	s_setprio 1
	v_mfma_f32_16x16x32_bf16 v[10:13], v[200:203], v[40:43], v[12:15]
	v_mfma_f32_16x16x32_bf16 v[14:17], v[208:211], v[40:43], v[16:19]
	v_mfma_f32_16x16x32_bf16 v[40:43], v[200:203], v[124:127], v[48:51]
	v_mfma_f32_16x16x32_bf16 v[220:223], v[204:207], v[128:131], v[40:43]
	v_mfma_f32_16x16x32_bf16 v[40:43], v[208:211], v[124:127], v[92:95]
	v_mfma_f32_16x16x32_bf16 v[224:227], v[212:215], v[128:131], v[40:43]
	v_mfma_f32_16x16x32_bf16 v[40:43], v[200:203], v[184:187], v[96:99]
	v_mfma_f32_16x16x32_bf16 v[228:231], v[204:207], v[188:191], v[40:43]
	v_mfma_f32_16x16x32_bf16 v[40:43], v[208:211], v[184:187], v[104:107]
	v_mfma_f32_16x16x32_bf16 v[184:187], v[212:215], v[188:191], v[40:43]
	v_mfma_f32_16x16x32_bf16 v[40:43], v[200:203], v[192:195], v[84:87]
	v_mfma_f32_16x16x32_bf16 v[10:13], v[204:207], v[44:47], v[10:13]
	v_mfma_f32_16x16x32_bf16 v[14:17], v[212:215], v[44:47], v[14:17]
	v_mfma_f32_16x16x32_bf16 v[188:191], v[204:207], v[196:199], v[40:43]
	v_mfma_f32_16x16x32_bf16 v[40:43], v[208:211], v[192:195], v[88:91]
	v_mfma_f32_16x16x32_bf16 v[192:195], v[212:215], v[196:199], v[40:43]
	s_setprio 0
	s_barrier
	ds_read_b128 v[196:199], v147
	ds_read_b128 v[200:203], v147 offset:1024
	ds_read_b128 v[204:207], v147 offset:2048
	ds_read_b128 v[208:211], v147 offset:3072
	s_mov_b32 m0, s80
	v_lshl_add_u64 v[18:19], v[252:253], 0, s[38:39]
	ds_read_b128 v[40:43], v175 offset:32768
	ds_read_b128 v[44:47], v175 offset:33792
	ds_read_b128 v[48:51], v175 offset:34816
	ds_read_b128 v[84:87], v175 offset:35840
	ds_read_b128 v[88:91], v175 offset:36864
	ds_read_b128 v[92:95], v175 offset:37888
	ds_read_b128 v[96:99], v175 offset:38912
	ds_read_b128 v[212:215], v175 offset:39936
	global_load_lds_dwordx4 v[18:19], off
	v_lshl_add_u64 v[18:19], v[252:253], 0, s[40:41]
	s_mov_b32 m0, s81
	s_nop 0
	global_load_lds_dwordx4 v[18:19], off
	s_waitcnt lgkmcnt(8)
	s_barrier
	s_waitcnt lgkmcnt(0)
	s_setprio 1
	s_waitcnt lgkmcnt(0)
	v_mfma_f32_16x16x32_bf16 v[52:55], v[196:199], v[40:43], v[52:55]
	v_mfma_f32_16x16x32_bf16 v[134:137], v[200:203], v[44:47], v[52:55]
	v_mfma_f32_16x16x32_bf16 v[52:55], v[204:207], v[40:43], v[56:59]
	v_mfma_f32_16x16x32_bf16 v[130:133], v[208:211], v[44:47], v[52:55]
	v_mfma_f32_16x16x32_bf16 v[52:55], v[196:199], v[48:51], v[60:63]
	v_mfma_f32_16x16x32_bf16 v[126:129], v[200:203], v[84:87], v[52:55]
	v_mfma_f32_16x16x32_bf16 v[52:55], v[204:207], v[48:51], v[64:67]
	v_mfma_f32_16x16x32_bf16 v[122:125], v[208:211], v[84:87], v[52:55]
	v_mfma_f32_16x16x32_bf16 v[52:55], v[196:199], v[88:91], v[68:71]
	v_mfma_f32_16x16x32_bf16 v[118:121], v[200:203], v[92:95], v[52:55]
	v_mfma_f32_16x16x32_bf16 v[52:55], v[204:207], v[88:91], v[72:75]
	v_mfma_f32_16x16x32_bf16 v[114:117], v[208:211], v[92:95], v[52:55]
	v_mfma_f32_16x16x32_bf16 v[52:55], v[196:199], v[96:99], v[76:79]
	v_mfma_f32_16x16x32_bf16 v[110:113], v[200:203], v[212:215], v[52:55]
	v_mfma_f32_16x16x32_bf16 v[52:55], v[204:207], v[96:99], v[80:83]
	v_mfma_f32_16x16x32_bf16 v[106:109], v[208:211], v[212:215], v[52:55]
	s_setprio 0
	s_barrier
	s_mov_b32 m0, vcc_hi
	v_lshl_add_u64 v[18:19], v[168:169], 0, s[48:49]
	ds_read_b128 v[70:73], v179
	ds_read_b128 v[78:81], v179 offset:1024
	ds_read_b128 v[232:235], v179 offset:2048
	ds_read_b128 v[236:239], v179 offset:3072
	global_load_lds_dwordx4 v[18:19], off
	v_lshl_add_u64 v[18:19], v[168:169], 0, s[50:51]
	s_mov_b32 m0, s0
	s_nop 0
	global_load_lds_dwordx4 v[18:19], off
	s_barrier
	s_waitcnt lgkmcnt(0)
	s_setprio 1
	s_waitcnt lgkmcnt(0)
	v_mfma_f32_16x16x32_bf16 v[18:21], v[232:235], v[40:43], v[20:23]
	v_mfma_f32_16x16x32_bf16 v[52:55], v[70:73], v[40:43], v[100:103]
	v_mfma_f32_16x16x32_bf16 v[58:61], v[236:239], v[44:47], v[18:21]
	v_mfma_f32_16x16x32_bf16 v[18:21], v[70:73], v[48:51], v[24:27]
	v_mfma_f32_16x16x32_bf16 v[62:65], v[78:81], v[44:47], v[52:55]
	v_mfma_f32_16x16x32_bf16 v[54:57], v[78:81], v[84:87], v[18:21]
	v_mfma_f32_16x16x32_bf16 v[18:21], v[232:235], v[48:51], v[28:31]
	v_mfma_f32_16x16x32_bf16 v[50:53], v[236:239], v[84:87], v[18:21]
	v_mfma_f32_16x16x32_bf16 v[18:21], v[70:73], v[88:91], v[32:35]
	v_mfma_f32_16x16x32_bf16 v[46:49], v[78:81], v[92:95], v[18:21]
	v_mfma_f32_16x16x32_bf16 v[18:21], v[232:235], v[88:91], v[36:39]
	v_mfma_f32_16x16x32_bf16 v[42:45], v[236:239], v[92:95], v[18:21]
	v_mfma_f32_16x16x32_bf16 v[18:21], v[70:73], v[96:99], v[164:167]
	v_mfma_f32_16x16x32_bf16 v[38:41], v[78:81], v[212:215], v[18:21]
	v_mfma_f32_16x16x32_bf16 v[18:21], v[232:235], v[96:99], v[180:183]
	v_mfma_f32_16x16x32_bf16 v[34:37], v[236:239], v[212:215], v[18:21]
	s_setprio 0
	s_mov_b32 m0, s83
	v_lshl_add_u64 v[26:27], v[252:253], 0, s[48:49]
	s_barrier
	s_nop 2
	ds_read_b128 v[18:21], v175 offset:49152
	ds_read_b128 v[22:25], v175 offset:50176
	ds_read_b128 v[164:167], v175 offset:51200
	ds_read_b128 v[180:183], v175 offset:52224
	ds_read_b128 v[212:215], v175 offset:53248
	ds_read_b128 v[240:243], v175 offset:54272
	ds_read_b128 v[244:247], v175 offset:55296
	ds_read_b128 v[248:251], v175 offset:56320
	global_load_lds_dwordx4 v[26:27], off
	v_lshl_add_u64 v[26:27], v[252:253], 0, s[52:53]
	s_mov_b32 m0, s87
	s_nop 0
	global_load_lds_dwordx4 v[26:27], off
	s_barrier
	s_waitcnt lgkmcnt(0)
	s_setprio 1
	s_waitcnt lgkmcnt(0)
	v_mfma_f32_16x16x32_bf16 v[26:29], v[196:199], v[18:21], v[216:219]
	v_mfma_f32_16x16x32_bf16 v[102:105], v[200:203], v[22:25], v[26:29]
	v_mfma_f32_16x16x32_bf16 v[26:29], v[204:207], v[18:21], v[138:141]
	v_mfma_f32_16x16x32_bf16 v[98:101], v[208:211], v[22:25], v[26:29]
	v_mfma_f32_16x16x32_bf16 v[26:29], v[196:199], v[164:167], v[148:151]
	v_mfma_f32_16x16x32_bf16 v[94:97], v[200:203], v[180:183], v[26:29]
	v_mfma_f32_16x16x32_bf16 v[26:29], v[204:207], v[164:167], v[152:155]
	v_mfma_f32_16x16x32_bf16 v[90:93], v[208:211], v[180:183], v[26:29]
	v_mfma_f32_16x16x32_bf16 v[26:29], v[196:199], v[212:215], v[156:159]
	v_mfma_f32_16x16x32_bf16 v[2:5], v[196:199], v[244:247], v[2:5]
	v_mfma_f32_16x16x32_bf16 v[86:89], v[200:203], v[240:243], v[26:29]
	v_mfma_f32_16x16x32_bf16 v[26:29], v[204:207], v[212:215], v[160:163]
	v_mfma_f32_16x16x32_bf16 v[74:77], v[200:203], v[248:251], v[2:5]
	v_mfma_f32_16x16x32_bf16 v[2:5], v[204:207], v[244:247], v[6:9]
	v_mfma_f32_16x16x32_bf16 v[82:85], v[208:211], v[240:243], v[26:29]
	v_mfma_f32_16x16x32_bf16 v[66:69], v[208:211], v[248:251], v[2:5]
	s_setprio 0
	s_barrier
	s_mov_b32 m0, s30
	s_nop 2
	v_lshl_add_u64 v[2:3], v[168:169], 0, s[54:55]
	global_load_lds_dwordx4 v[2:3], off
	v_lshl_add_u64 v[2:3], v[168:169], 0, s[56:57]
	s_mov_b32 m0, s31
	s_nop 0
	global_load_lds_dwordx4 v[2:3], off
	s_cmp_lg_u32 s100, 1
	s_cbranch_scc1 .Lp9w_skip
	s_mov_b32 s100, 0
	v_readfirstlane_b32 s101, v0
	s_cmp_lg_u32 s101, 0
	s_cbranch_scc1 .Lp9w_skip
	v_readlane_b32 s98, v254, 13
	v_readlane_b32 s99, v254, 14
	s_mov_b32 s32, 0x100000
	s_nop 4
.Lp9w_poll:
	v_mov_b32_e32 v255, 0x2b5d03c
	global_load_dword v255, v255, s[98:99] sc1
	s_waitcnt vmcnt(0)
	v_readfirstlane_b32 s101, v255
	s_cmp_ge_u32 s101, 0x100
	s_cbranch_scc1 .Lp9w_skip
	s_sleep 1
	s_sub_u32 s32, s32, 1
	s_cmp_lg_u32 s32, 0
	s_cbranch_scc1 .Lp9w_poll
.Lp9w_skip:
	s_waitcnt vmcnt(6)
	s_barrier
	s_setprio 1
	v_mfma_f32_16x16x32_bf16 v[2:5], v[70:73], v[18:21], v[10:13]
	v_mfma_f32_16x16x32_bf16 v[30:33], v[78:81], v[22:25], v[2:5]
	v_mfma_f32_16x16x32_bf16 v[2:5], v[232:235], v[18:21], v[14:17]
	v_mfma_f32_16x16x32_bf16 v[26:29], v[236:239], v[22:25], v[2:5]
	v_mfma_f32_16x16x32_bf16 v[2:5], v[70:73], v[164:167], v[220:223]
	v_mfma_f32_16x16x32_bf16 v[22:25], v[78:81], v[180:183], v[2:5]
	v_mfma_f32_16x16x32_bf16 v[2:5], v[232:235], v[164:167], v[224:227]
	v_mfma_f32_16x16x32_bf16 v[18:21], v[236:239], v[180:183], v[2:5]
	v_mfma_f32_16x16x32_bf16 v[2:5], v[70:73], v[212:215], v[228:231]
	v_mfma_f32_16x16x32_bf16 v[14:17], v[78:81], v[240:243], v[2:5]
	v_mfma_f32_16x16x32_bf16 v[2:5], v[232:235], v[212:215], v[184:187]
	v_mfma_f32_16x16x32_bf16 v[10:13], v[236:239], v[240:243], v[2:5]
	v_mfma_f32_16x16x32_bf16 v[2:5], v[70:73], v[244:247], v[188:191]
	v_mfma_f32_16x16x32_bf16 v[6:9], v[78:81], v[248:251], v[2:5]
	v_mfma_f32_16x16x32_bf16 v[2:5], v[232:235], v[244:247], v[192:195]
	v_mfma_f32_16x16x32_bf16 v[2:5], v[236:239], v[248:251], v[2:5]
	s_setprio 0
	s_andn2_b64 vcc, exec, s[58:59]
	s_barrier
	s_cbranch_vccnz .LBB0_1237
	s_barrier
